# GEMM phase prologues: all 14 first-tile DMA loads (K-tiles 0 and 1) issued before the first wait/barrier instead of 8 + wait + barrier + 6
# baseline (speedup 1.0000x reference)
.LBB0_161:
	s_mov_b64 s[18:19], 0x80
	s_add_i32 m0, s39, 0x18000
	v_lshl_add_u64 v[6:7], v[6:7], 0, s[18:19]
	global_load_lds_dwordx4 v[6:7], off
	v_lshl_add_u64 v[4:5], v[4:5], 0, s[18:19]
	s_add_i32 m0, s39, 0x1a000
	s_add_i32 s44, s39, 0x8000
	s_add_i32 s45, s39, 0xa000
	global_load_lds_dwordx4 v[4:5], off
	v_lshl_add_u64 v[0:1], v[0:1], 0, s[18:19]
	s_mov_b32 m0, s44
	s_add_u32 s20, s34, 0x80080
	global_load_lds_dwordx4 v[0:1], off
	v_lshl_add_u64 v[0:1], v[2:3], 0, s[18:19]
	s_mov_b32 m0, s45
	s_addc_u32 s21, s35, 0
	global_load_lds_dwordx4 v[0:1], off
	s_add_i32 m0, s39, 0x1c000
	v_lshl_add_u64 v[0:1], s[20:21], 0, v[132:133]
	global_load_lds_dwordx4 v[0:1], off
	v_lshl_add_u64 v[0:1], s[20:21], 0, v[128:129]
	s_add_i32 m0, s39, 0x1e000
	s_sext_i32_i16 s9, s6
	global_load_lds_dwordx4 v[0:1], off
	s_waitcnt vmcnt(8)
	s_barrier
	v_and_b32_e32 v0, 15, v8
	v_or_b32_e32 v148, s87, v0
	v_lshlrev_b32_e32 v3, 6, v148
	v_and_b32_e32 v4, 48, v8
	s_movk_i32 s6, 0x3c0
	v_ashrrev_i32_e32 v2, 6, v8
	v_and_or_b32 v3, v3, s6, v4
	v_lshl_or_b32 v0, v0, 6, v4
	v_readlane_b32 s6, v250, 2
	v_lshlrev_b32_e32 v4, 2, v8
	v_lshl_add_u32 v5, v2, 10, s86
	v_add_lshl_u32 v2, v2, s6, 10
	v_and_b32_e32 v4, 32, v4
	v_ashrrev_i32_e32 v1, 1, v8
	v_bitop3_b32 v149, v0, v2, v4 bitop3:0xde
	v_lshlrev_b32_e32 v0, 15, v12
	v_and_b32_e32 v1, -8, v1
	v_readlane_b32 s6, v250, 1
	v_and_b32_e32 v0, 0xffff0000, v0
	v_lshl_add_u32 v0, v13, 12, v0
	v_add_u32_e32 v150, s6, v1
	v_and_b32_e32 v1, 1, v12
	v_lshl_or_b32 v0, v1, 6, v0
	v_lshl_add_u32 v136, v14, 1, v0
	v_lshlrev_b32_e32 v0, 15, v9
	v_lshlrev_b32_e32 v6, 2, v148
	v_and_b32_e32 v0, 0xffff0000, v0
	v_and_b32_e32 v6, 32, v6
	s_waitcnt vmcnt(6)
	s_cmpk_lt_u32 s33, 0x100
	v_lshl_add_u32 v0, v10, 12, v0
	v_and_b32_e32 v1, 1, v9
	v_bitop3_b32 v3, v3, v5, v6 bitop3:0xde
	s_cselect_b64 s[20:21], -1, 0
	v_lshl_or_b32 v0, v1, 6, v0
	s_add_i32 s60, 0, 0x10000
	s_add_i32 s61, 0, 0x14000
	s_ashr_i32 s58, s46, 31
	s_mov_b32 s59, s46
	v_mov_b32_e32 v137, v133
	v_lshl_add_u32 v138, v11, 1, v0
	v_mov_b32_e32 v139, v133
	v_mov_b64_e32 v[140:141], 0x580
	v_mov_b64_e32 v[142:143], 0x57f
	v_add_u32_e32 v151, s60, v149
	v_add_u32_e32 v152, s61, v149
	v_add_u32_e32 v153, 0, v3
	v_mov_b32_e32 v154, 0x358637bd
	s_mov_b32 s67, 0x800000
	s_movk_i32 s69, 0x2c00
	s_barrier
	s_branch .LBB0_164

.LBB0_346:
	v_and_b32_e32 v187, 15, v184
	v_or_b32_e32 v14, s87, v187
	v_lshlrev_b32_e32 v15, 6, v14
	s_mov_b64 s[18:19], 0x80
	v_and_b32_e32 v15, 0x3c0, v15
	v_and_b32_e32 v186, 48, v184
	v_and_b32_e32 v17, 0xfffffc00, v185
	v_lshlrev_b32_e32 v14, 2, v14
	s_add_i32 m0, s44, 0x18000
	v_lshl_add_u64 v[6:7], v[6:7], 0, s[18:19]
	s_sext_i32_i8 s73, s6
	v_or_b32_e32 v16, v15, v186
	v_add_u32_e32 v18, s86, v17
	v_and_b32_e32 v14, 32, v14
	v_readlane_b32 s6, v250, 8
	global_load_lds_dwordx4 v[6:7], off
	v_lshl_add_u64 v[4:5], v[4:5], 0, s[18:19]
	s_add_i32 m0, s44, 0x1a000
	s_add_i32 s74, s44, 0x8000
	s_add_i32 s75, s44, 0xa000
	v_bitop3_b32 v188, v15, v14, v186 bitop3:0x36
	v_bitop3_b32 v14, v16, v18, v14 bitop3:0xde
	v_add_u32_e32 v16, s6, v17
	global_load_lds_dwordx4 v[4:5], off
	v_lshl_add_u64 v[0:1], v[0:1], 0, s[18:19]
	s_mov_b32 m0, s74
	s_add_u32 s6, s30, 0x160080
	global_load_lds_dwordx4 v[0:1], off
	v_lshl_add_u64 v[0:1], v[2:3], 0, s[18:19]
	s_mov_b32 m0, s75
	s_addc_u32 s7, s31, 0
	global_load_lds_dwordx4 v[0:1], off
	s_add_i32 m0, s44, 0x1c000
	v_lshl_add_u64 v[0:1], s[6:7], 0, v[170:171]
	global_load_lds_dwordx4 v[0:1], off
	v_lshl_add_u64 v[0:1], s[6:7], 0, v[174:175]
	s_add_i32 m0, s44, 0x1e000
	v_lshlrev_b32_e32 v17, 2, v184
	global_load_lds_dwordx4 v[0:1], off
	s_waitcnt vmcnt(0)
	s_waitcnt vmcnt(8)
	s_barrier
	v_and_b32_e32 v0, 0xffff0, v8
	v_add_lshl_u32 v0, v9, v0, 12
	s_waitcnt vmcnt(6)
	v_lshl_add_u32 v162, v10, 1, v0
	v_and_b32_e32 v0, 0xffff0, v11
	v_lshl_or_b32 v15, v187, 6, v186
	v_and_b32_e32 v17, 32, v17
	s_cmpk_lt_u32 s33, 0x100
	v_add_lshl_u32 v0, v12, v0, 12
	v_bitop3_b32 v189, v15, v16, v17 bitop3:0xde
	s_cselect_b64 s[20:21], -1, 0
	v_lshl_add_u32 v164, v13, 1, v0
	v_mov_b32_e32 v163, v161
	v_mov_b32_e32 v165, v161
	v_mov_b64_e32 v[166:167], 0x100
	v_mov_b64_e32 v[168:169], 0xff
	v_add_u32_e32 v190, 0, v14
	v_mov_b32_e32 v0, v161
	v_mov_b32_e32 v1, v161
	v_mov_b32_e32 v2, v161
	v_mov_b32_e32 v3, v161
	v_mov_b32_e32 v4, v161
	v_mov_b32_e32 v5, v161
	v_mov_b32_e32 v6, v161
	v_mov_b32_e32 v7, v161
	v_mov_b32_e32 v16, v161
	v_mov_b32_e32 v17, v161
	v_mov_b32_e32 v18, v161
	v_mov_b32_e32 v19, v161
	v_mov_b32_e32 v20, v161
	v_mov_b32_e32 v21, v161
	v_mov_b32_e32 v22, v161
	v_mov_b32_e32 v23, v161
	v_mov_b32_e32 v32, v161
	v_mov_b32_e32 v33, v161
	v_mov_b32_e32 v34, v161
	v_mov_b32_e32 v35, v161
	v_mov_b32_e32 v36, v161
	v_mov_b32_e32 v37, v161
	v_mov_b32_e32 v38, v161
	v_mov_b32_e32 v39, v161
	v_mov_b32_e32 v48, v161
	v_mov_b32_e32 v49, v161
	v_mov_b32_e32 v50, v161
	v_mov_b32_e32 v51, v161
	v_mov_b32_e32 v52, v161
	v_mov_b32_e32 v53, v161
	v_mov_b32_e32 v54, v161
	v_mov_b32_e32 v55, v161
	v_mov_b32_e32 v8, v161
	v_mov_b32_e32 v9, v161
	v_mov_b32_e32 v10, v161
	v_mov_b32_e32 v11, v161
	v_mov_b32_e32 v12, v161
	v_mov_b32_e32 v13, v161
	v_mov_b32_e32 v14, v161
	v_mov_b32_e32 v15, v161
	v_mov_b32_e32 v24, v161
	v_mov_b32_e32 v25, v161
	v_mov_b32_e32 v26, v161
	v_mov_b32_e32 v27, v161
	v_mov_b32_e32 v28, v161
	v_mov_b32_e32 v29, v161
	v_mov_b32_e32 v30, v161
	v_mov_b32_e32 v31, v161
	v_mov_b32_e32 v40, v161
	v_mov_b32_e32 v41, v161
	v_mov_b32_e32 v42, v161
	v_mov_b32_e32 v43, v161
	v_mov_b32_e32 v44, v161
	v_mov_b32_e32 v45, v161
	v_mov_b32_e32 v46, v161
	v_mov_b32_e32 v47, v161
	v_mov_b32_e32 v56, v161
	v_mov_b32_e32 v57, v161
	v_mov_b32_e32 v58, v161
	v_mov_b32_e32 v59, v161
	v_mov_b32_e32 v60, v161
	v_mov_b32_e32 v61, v161
	v_mov_b32_e32 v62, v161
	v_mov_b32_e32 v63, v161
	v_mov_b32_e32 v64, v161
	v_mov_b32_e32 v65, v161
	v_mov_b32_e32 v66, v161
	v_mov_b32_e32 v67, v161
	v_mov_b32_e32 v68, v161
	v_mov_b32_e32 v69, v161
	v_mov_b32_e32 v70, v161
	v_mov_b32_e32 v71, v161
	v_mov_b32_e32 v80, v161
	v_mov_b32_e32 v81, v161
	v_mov_b32_e32 v82, v161
	v_mov_b32_e32 v83, v161
	v_mov_b32_e32 v84, v161
	v_mov_b32_e32 v85, v161
	v_mov_b32_e32 v86, v161
	v_mov_b32_e32 v87, v161
	v_mov_b32_e32 v96, v161
	v_mov_b32_e32 v97, v161
	v_mov_b32_e32 v98, v161
	v_mov_b32_e32 v99, v161
	v_mov_b32_e32 v100, v161
	v_mov_b32_e32 v101, v161
	v_mov_b32_e32 v102, v161
	v_mov_b32_e32 v103, v161
	v_mov_b32_e32 v112, v161
	v_mov_b32_e32 v113, v161
	v_mov_b32_e32 v114, v161
	v_mov_b32_e32 v115, v161
	v_mov_b32_e32 v116, v161
	v_mov_b32_e32 v117, v161
	v_mov_b32_e32 v118, v161
	v_mov_b32_e32 v119, v161
	v_mov_b32_e32 v72, v161
	v_mov_b32_e32 v73, v161
	v_mov_b32_e32 v74, v161
	v_mov_b32_e32 v75, v161
	v_mov_b32_e32 v76, v161
	v_mov_b32_e32 v77, v161
	v_mov_b32_e32 v78, v161
	v_mov_b32_e32 v79, v161
	v_mov_b32_e32 v88, v161
	v_mov_b32_e32 v89, v161
	v_mov_b32_e32 v90, v161
	v_mov_b32_e32 v91, v161
	v_mov_b32_e32 v92, v161
	v_mov_b32_e32 v93, v161
	v_mov_b32_e32 v94, v161
	v_mov_b32_e32 v95, v161
	v_mov_b32_e32 v104, v161
	v_mov_b32_e32 v105, v161
	v_mov_b32_e32 v106, v161
	v_mov_b32_e32 v107, v161
	v_mov_b32_e32 v108, v161
	v_mov_b32_e32 v109, v161
	v_mov_b32_e32 v110, v161
	v_mov_b32_e32 v111, v161
	v_mov_b32_e32 v120, v161
	v_mov_b32_e32 v121, v161
	v_mov_b32_e32 v122, v161
	v_mov_b32_e32 v123, v161
	v_mov_b32_e32 v124, v161
	v_mov_b32_e32 v125, v161
	v_mov_b32_e32 v126, v161
	v_mov_b32_e32 v127, v161
	s_barrier
	s_branch .LBB0_349

.LBB0_448:
	s_mov_b64 s[18:19], 0x80
	s_add_i32 m0, s60, 0x18000
	v_lshl_add_u64 v[6:7], v[6:7], 0, s[18:19]
	global_load_lds_dwordx4 v[6:7], off
	v_lshl_add_u64 v[4:5], v[4:5], 0, s[18:19]
	s_add_i32 m0, s60, 0x1a000
	s_add_i32 s73, s60, 0x8000
	s_add_i32 s74, s60, 0xa000
	global_load_lds_dwordx4 v[4:5], off
	v_lshl_add_u64 v[0:1], v[0:1], 0, s[18:19]
	s_mov_b32 m0, s73
	s_add_u32 s6, s38, 0x80080
	global_load_lds_dwordx4 v[0:1], off
	v_lshl_add_u64 v[0:1], v[2:3], 0, s[18:19]
	s_mov_b32 m0, s74
	s_addc_u32 s7, s39, 0
	global_load_lds_dwordx4 v[0:1], off
	s_add_i32 m0, s60, 0x1c000
	v_lshl_add_u64 v[0:1], s[6:7], 0, v[130:131]
	global_load_lds_dwordx4 v[0:1], off
	v_lshl_add_u64 v[0:1], s[6:7], 0, v[134:135]
	s_add_i32 m0, s60, 0x1e000
	v_and_b32_e32 v158, 15, v8
	global_load_lds_dwordx4 v[0:1], off
	s_waitcnt vmcnt(8)
	s_barrier
	v_or_b32_e32 v0, s87, v158
	v_lshlrev_b32_e32 v3, 6, v0
	v_and_b32_e32 v4, 48, v8
	s_movk_i32 s6, 0x3c0
	v_ashrrev_i32_e32 v1, 1, v8
	v_ashrrev_i32_e32 v2, 6, v8
	v_and_or_b32 v3, v3, s6, v4
	v_lshlrev_b32_e32 v0, 2, v0
	v_readlane_b32 s6, v250, 2
	v_and_b32_e32 v1, -8, v1
	v_lshl_add_u32 v5, v2, 10, s86
	v_and_b32_e32 v0, 32, v0
	v_add_lshl_u32 v2, v2, s6, 10
	v_readlane_b32 s6, v250, 1
	v_bitop3_b32 v0, v3, v5, v0 bitop3:0xde
	v_lshl_or_b32 v3, v158, 6, v4
	v_lshlrev_b32_e32 v4, 2, v8
	v_add_u32_e32 v136, s6, v1
	v_lshlrev_b32_e32 v1, 15, v9
	v_and_b32_e32 v4, 32, v4
	v_and_b32_e32 v1, 0xffff0000, v1
	v_bitop3_b32 v159, v3, v2, v4 bitop3:0xde
	v_lshl_add_u32 v1, v10, 12, v1
	v_and_b32_e32 v2, 1, v9
	v_lshl_or_b32 v1, v2, 6, v1
	v_lshl_add_u32 v138, v11, 1, v1
	v_lshlrev_b32_e32 v1, 15, v12
	v_and_b32_e32 v1, 0xffff0000, v1
	s_waitcnt vmcnt(6)
	s_cmpk_lt_u32 s33, 0x100
	v_lshl_add_u32 v1, v13, 12, v1
	v_and_b32_e32 v2, 1, v12
	s_cselect_b64 s[20:21], -1, 0
	v_lshl_or_b32 v1, v2, 6, v1
	s_add_i32 s78, 0, 0x10000
	s_add_i32 s79, 0, 0x14000
	v_ashrrev_i32_e32 v137, 31, v136
	s_ashr_i32 s75, s46, 31
	s_mov_b32 s76, s46
	s_ashr_i32 s77, s2, 31
	v_mov_b32_e32 v139, v131
	v_lshl_add_u32 v140, v14, 1, v1
	v_mov_b32_e32 v141, v131
	v_mov_b64_e32 v[142:143], 0x280
	v_mov_b64_e32 v[144:145], 0x27f
	s_mov_b64 s[22:23], 0x100
	v_add_u32_e32 v160, s78, v159
	v_add_u32_e32 v161, s79, v159
	v_add_u32_e32 v162, 0, v0
	v_mov_b32_e32 v163, 0x358637bd
	s_mov_b32 s80, 0x800000
	s_movk_i32 s81, 0x1800
	s_movk_i32 s83, 0x1000
	v_mov_b32_e32 v164, 0xfcf
	s_mov_b32 s96, 0
	s_barrier
	s_branch .LBB0_451

.LBB0_532:
	s_mov_b64 s[16:17], 0x80
	s_add_i32 m0, s35, 0x18000
	v_lshl_add_u64 v[6:7], v[6:7], 0, s[16:17]
	global_load_lds_dwordx4 v[6:7], off
	v_lshl_add_u64 v[4:5], v[4:5], 0, s[16:17]
	s_add_i32 m0, s35, 0x1a000
	s_add_i32 s61, s35, 0x8000
	s_add_i32 s67, s35, 0xa000
	global_load_lds_dwordx4 v[4:5], off
	v_lshl_add_u64 v[0:1], v[0:1], 0, s[16:17]
	s_mov_b32 m0, s61
	s_add_u32 s18, s36, 0x80080
	global_load_lds_dwordx4 v[0:1], off
	v_lshl_add_u64 v[0:1], v[2:3], 0, s[16:17]
	s_mov_b32 m0, s67
	s_addc_u32 s19, s37, 0
	global_load_lds_dwordx4 v[0:1], off
	s_add_i32 m0, s35, 0x1c000
	v_lshl_add_u64 v[0:1], s[18:19], 0, v[134:135]
	global_load_lds_dwordx4 v[0:1], off
	v_lshl_add_u64 v[0:1], s[18:19], 0, v[138:139]
	s_add_i32 m0, s35, 0x1e000
	s_sext_i32_i16 s78, s6
	global_load_lds_dwordx4 v[0:1], off
	s_waitcnt vmcnt(8)
	s_barrier
	v_and_b32_e32 v0, 15, v8
	v_or_b32_e32 v164, s87, v0
	v_lshlrev_b32_e32 v3, 6, v164
	v_and_b32_e32 v4, 48, v8
	s_movk_i32 s6, 0x3c0
	v_ashrrev_i32_e32 v2, 6, v8
	v_and_or_b32 v3, v3, s6, v4
	v_lshl_or_b32 v0, v0, 6, v4
	v_readlane_b32 s6, v250, 2
	v_lshlrev_b32_e32 v4, 2, v8
	v_lshl_add_u32 v5, v2, 10, s86
	v_add_lshl_u32 v2, v2, s6, 10
	v_and_b32_e32 v4, 32, v4
	v_ashrrev_i32_e32 v1, 1, v8
	v_bitop3_b32 v165, v0, v2, v4 bitop3:0xde
	v_lshlrev_b32_e32 v0, 15, v9
	v_and_b32_e32 v1, -8, v1
	v_readlane_b32 s6, v250, 1
	v_and_b32_e32 v0, 0xffff0000, v0
	v_lshl_add_u32 v0, v10, 12, v0
	v_add_u32_e32 v166, s6, v1
	v_and_b32_e32 v1, 1, v9
	v_lshl_or_b32 v0, v1, 6, v0
	v_lshl_add_u32 v140, v11, 1, v0
	v_lshlrev_b32_e32 v0, 15, v12
	v_lshlrev_b32_e32 v6, 2, v164
	v_and_b32_e32 v0, 0xffff0000, v0
	v_and_b32_e32 v6, 32, v6
	s_waitcnt vmcnt(6)
	s_cmpk_lt_u32 s33, 0x100
	v_lshl_add_u32 v0, v13, 12, v0
	v_and_b32_e32 v1, 1, v12
	v_bitop3_b32 v3, v3, v5, v6 bitop3:0xde
	s_cselect_b64 s[18:19], -1, 0
	v_lshl_or_b32 v0, v1, 6, v0
	s_add_i32 s75, 0, 0x10000
	s_add_i32 s76, 0, 0x14000
	s_ashr_i32 s69, s46, 31
	s_mov_b32 s74, s46
	v_mov_b32_e32 v141, v135
	v_lshl_add_u32 v142, v14, 1, v0
	v_mov_b32_e32 v143, v135
	v_mov_b64_e32 v[144:145], 0x80
	v_mov_b64_e32 v[146:147], 0x7f
	v_add_u32_e32 v167, s75, v165
	v_add_u32_e32 v168, s76, v165
	v_add_u32_e32 v169, 0, v3
	s_mov_b32 s20, 0x3a000000
	s_mov_b32 s77, 0x800000
	s_mov_b32 s22, 0x45800000
	s_barrier
	s_branch .LBB0_535

.LBB0_938:
	s_mov_b64 s[18:19], 0x80
	s_add_i32 m0, s15, 0x18000
	v_lshl_add_u64 v[6:7], v[6:7], 0, s[18:19]
	global_load_lds_dwordx4 v[6:7], off
	v_lshl_add_u64 v[4:5], v[4:5], 0, s[18:19]
	s_add_i32 m0, s15, 0x1a000
	s_add_i32 s70, s15, 0x8000
	s_add_i32 s71, s15, 0xa000
	global_load_lds_dwordx4 v[4:5], off
	v_lshl_add_u64 v[0:1], v[0:1], 0, s[18:19]
	s_mov_b32 m0, s70
	s_add_u32 s8, s24, 0x80080
	global_load_lds_dwordx4 v[0:1], off
	v_lshl_add_u64 v[0:1], v[2:3], 0, s[18:19]
	s_mov_b32 m0, s71
	s_addc_u32 s9, s25, 0
	global_load_lds_dwordx4 v[0:1], off
	s_add_i32 m0, s15, 0x1c000
	v_lshl_add_u64 v[0:1], s[8:9], 0, v[178:179]
	global_load_lds_dwordx4 v[0:1], off
	v_lshl_add_u64 v[0:1], s[8:9], 0, v[182:183]
	s_add_i32 m0, s15, 0x1e000
	v_and_b32_e32 v192, 15, v189
	global_load_lds_dwordx4 v[0:1], off
	s_waitcnt vmcnt(8)
	s_barrier
	v_or_b32_e32 v0, s87, v192
	v_lshlrev_b32_e32 v1, 6, v0
	v_and_b32_e32 v1, 0x3c0, v1
	v_and_b32_e32 v191, 48, v189
	v_and_b32_e32 v3, 0xfffffc00, v190
	v_lshlrev_b32_e32 v0, 2, v0
	v_or_b32_e32 v2, v1, v191
	v_add_u32_e32 v4, s86, v3
	v_and_b32_e32 v0, 32, v0
	v_bitop3_b32 v4, v2, v4, v0 bitop3:0xde
	v_readlane_b32 s4, v250, 8
	v_lshlrev_b32_e32 v2, 2, v189
	v_bitop3_b32 v193, v1, v0, v191 bitop3:0x36
	v_lshl_or_b32 v0, v192, 6, v191
	v_add_u32_e32 v1, s4, v3
	v_and_b32_e32 v2, 32, v2
	v_bitop3_b32 v194, v0, v1, v2 bitop3:0xde
	v_and_b32_e32 v0, 0xffff0, v8
	v_add_u32_e32 v0, v9, v0
	v_lshl_add_u32 v170, v0, 12, v10
	v_and_b32_e32 v0, 0xffff0, v11
	s_waitcnt vmcnt(6)
	v_add_u32_e32 v0, v12, v0
	v_mov_b32_e32 v2, v169
	v_mov_b32_e32 v3, v169
	s_cmpk_lt_u32 s33, 0x100
	v_lshl_add_u32 v172, v0, 12, v13
	v_mov_b32_e32 v0, v169
	v_mov_b32_e32 v1, v169
	v_add_u32_e32 v195, 0, v4
	v_mov_b64_e32 v[6:7], v[2:3]
	s_waitcnt vmcnt(0)
	v_mov_b64_e32 v[18:19], v[2:3]
	v_mov_b64_e32 v[22:23], v[2:3]
	v_mov_b64_e32 v[34:35], v[2:3]
	v_mov_b64_e32 v[38:39], v[2:3]
	v_mov_b64_e32 v[50:51], v[2:3]
	v_mov_b64_e32 v[54:55], v[2:3]
	v_mov_b64_e32 v[10:11], v[2:3]
	v_mov_b64_e32 v[14:15], v[2:3]
	v_mov_b64_e32 v[26:27], v[2:3]
	v_mov_b64_e32 v[30:31], v[2:3]
	v_mov_b64_e32 v[42:43], v[2:3]
	v_mov_b64_e32 v[46:47], v[2:3]
	v_mov_b64_e32 v[58:59], v[2:3]
	v_mov_b64_e32 v[62:63], v[2:3]
	v_mov_b64_e32 v[66:67], v[2:3]
	v_mov_b64_e32 v[70:71], v[2:3]
	v_mov_b64_e32 v[82:83], v[2:3]
	v_mov_b64_e32 v[86:87], v[2:3]
	v_mov_b64_e32 v[98:99], v[2:3]
	v_mov_b64_e32 v[102:103], v[2:3]
	v_mov_b64_e32 v[118:119], v[2:3]
	v_mov_b64_e32 v[122:123], v[2:3]
	v_mov_b64_e32 v[74:75], v[2:3]
	v_mov_b64_e32 v[78:79], v[2:3]
	v_mov_b64_e32 v[90:91], v[2:3]
	v_mov_b64_e32 v[94:95], v[2:3]
	v_mov_b64_e32 v[110:111], v[2:3]
	v_mov_b64_e32 v[114:115], v[2:3]
	v_mov_b64_e32 v[130:131], v[2:3]
	v_mov_b64_e32 v[134:135], v[2:3]
	s_sext_i32_i8 s72, s6
	s_mov_b64 s[20:21], 0x80080
	s_cselect_b64 s[22:23], -1, 0
	v_mov_b32_e32 v171, v169
	v_mov_b32_e32 v173, v169
	s_mov_b32 s62, 0
	v_mov_b64_e32 v[174:175], 0x100
	v_mov_b64_e32 v[176:177], 0xff
	v_mov_b64_e32 v[4:5], v[0:1]
	v_mov_b64_e32 v[16:17], v[0:1]
	v_mov_b64_e32 v[20:21], v[0:1]
	v_mov_b64_e32 v[32:33], v[0:1]
	v_mov_b64_e32 v[36:37], v[0:1]
	v_mov_b64_e32 v[48:49], v[0:1]
	v_mov_b64_e32 v[52:53], v[0:1]
	v_mov_b64_e32 v[8:9], v[0:1]
	v_mov_b64_e32 v[12:13], v[0:1]
	v_mov_b64_e32 v[24:25], v[0:1]
	v_mov_b64_e32 v[28:29], v[0:1]
	v_mov_b64_e32 v[40:41], v[0:1]
	v_mov_b64_e32 v[44:45], v[0:1]
	v_mov_b64_e32 v[56:57], v[0:1]
	v_mov_b64_e32 v[60:61], v[0:1]
	v_mov_b64_e32 v[64:65], v[0:1]
	v_mov_b64_e32 v[68:69], v[0:1]
	v_mov_b64_e32 v[80:81], v[0:1]
	v_mov_b64_e32 v[84:85], v[0:1]
	v_mov_b64_e32 v[96:97], v[0:1]
	v_mov_b64_e32 v[100:101], v[0:1]
	v_mov_b64_e32 v[116:117], v[0:1]
	v_mov_b64_e32 v[120:121], v[0:1]
	v_mov_b64_e32 v[72:73], v[0:1]
	v_mov_b64_e32 v[76:77], v[0:1]
	v_mov_b64_e32 v[88:89], v[0:1]
	v_mov_b64_e32 v[92:93], v[0:1]
	v_mov_b64_e32 v[108:109], v[0:1]
	v_mov_b64_e32 v[112:113], v[0:1]
	v_mov_b64_e32 v[128:129], v[0:1]
	v_mov_b64_e32 v[132:133], v[0:1]
	s_barrier
	s_branch .LBB0_941

.LBB0_987:
	s_mov_b64 s[14:15], 0x80
	s_add_i32 m0, s90, 0x18000
	v_lshl_add_u64 v[6:7], v[6:7], 0, s[14:15]
	global_load_lds_dwordx4 v[6:7], off
	v_lshl_add_u64 v[4:5], v[4:5], 0, s[14:15]
	s_add_i32 m0, s90, 0x1a000
	s_add_i32 s75, s90, 0x8000
	s_add_i32 s76, s90, 0xa000
	global_load_lds_dwordx4 v[4:5], off
	v_lshl_add_u64 v[0:1], v[0:1], 0, s[14:15]
	s_mov_b32 m0, s75
	s_add_u32 s16, s28, 0x10080
	global_load_lds_dwordx4 v[0:1], off
	v_lshl_add_u64 v[0:1], v[2:3], 0, s[14:15]
	s_mov_b32 m0, s76
	s_addc_u32 s17, s29, 0
	global_load_lds_dwordx4 v[0:1], off
	s_add_i32 m0, s90, 0x1c000
	v_lshl_add_u64 v[0:1], s[16:17], 0, v[130:131]
	global_load_lds_dwordx4 v[0:1], off
	v_lshl_add_u64 v[0:1], s[16:17], 0, v[134:135]
	s_add_i32 m0, s90, 0x1e000
	s_sext_i32_i8 s81, s6
	global_load_lds_dwordx4 v[0:1], off
	s_waitcnt vmcnt(8)
	s_barrier
	v_and_b32_e32 v0, 15, v8
	v_or_b32_e32 v140, s87, v0
	v_lshlrev_b32_e32 v3, 6, v140
	v_and_b32_e32 v4, 48, v8
	s_movk_i32 s6, 0x3c0
	v_ashrrev_i32_e32 v2, 6, v8
	v_and_or_b32 v3, v3, s6, v4
	v_lshlrev_b32_e32 v6, 2, v140
	v_lshl_or_b32 v0, v0, 6, v4
	v_readlane_b32 s6, v250, 2
	v_lshlrev_b32_e32 v4, 2, v8
	v_ashrrev_i32_e32 v1, 1, v8
	v_lshl_add_u32 v5, v2, 10, s86
	v_and_b32_e32 v6, 32, v6
	v_add_lshl_u32 v2, v2, s6, 10
	v_and_b32_e32 v4, 32, v4
	s_waitcnt vmcnt(6)
	s_cmpk_lt_u32 s33, 0x100
	v_and_b32_e32 v1, -8, v1
	v_bitop3_b32 v3, v3, v5, v6 bitop3:0xde
	v_bitop3_b32 v141, v0, v2, v4 bitop3:0xde
	s_cselect_b64 s[16:17], -1, 0
	v_readlane_b32 s6, v250, 1
	s_add_i32 s79, 0, 0x10000
	s_add_i32 s80, 0, 0x14000
	v_add_u32_e32 v142, s6, v1
	s_ashr_i32 s77, s46, 31
	s_mov_b32 s78, s46
	v_mov_b64_e32 v[136:137], 0x100
	v_mov_b64_e32 v[138:139], 0xff
	v_add_u32_e32 v143, s79, v141
	v_add_u32_e32 v144, s80, v141
	v_add_u32_e32 v145, 0, v3
	s_barrier
	s_waitcnt vmcnt(0)
	s_branch .LBB0_990

.LBB0_1061:
	s_mov_b64 s[16:17], 0x80
	s_add_i32 m0, s40, 0x18000
	v_lshl_add_u64 v[6:7], v[6:7], 0, s[16:17]
	global_load_lds_dwordx4 v[6:7], off
	v_lshl_add_u64 v[4:5], v[4:5], 0, s[16:17]
	s_add_i32 m0, s40, 0x1a000
	s_add_i32 s61, s40, 0x8000
	s_add_i32 s62, s40, 0xa000
	global_load_lds_dwordx4 v[4:5], off
	v_lshl_add_u64 v[0:1], v[0:1], 0, s[16:17]
	s_mov_b32 m0, s61
	s_add_u32 s18, s30, 0x40080
	global_load_lds_dwordx4 v[0:1], off
	v_lshl_add_u64 v[0:1], v[2:3], 0, s[16:17]
	s_mov_b32 m0, s62
	s_addc_u32 s19, s31, 0
	global_load_lds_dwordx4 v[0:1], off
	s_add_i32 m0, s40, 0x1c000
	v_lshl_add_u64 v[0:1], s[18:19], 0, v[164:165]
	global_load_lds_dwordx4 v[0:1], off
	v_lshl_add_u64 v[0:1], s[18:19], 0, v[160:161]
	s_add_i32 m0, s40, 0x1e000
	s_sext_i32_i16 s9, s6
	global_load_lds_dwordx4 v[0:1], off
	s_waitcnt vmcnt(8)
	s_barrier
	v_and_b32_e32 v0, 15, v9
	v_or_b32_e32 v185, s87, v0
	v_lshlrev_b32_e32 v3, 6, v185
	v_and_b32_e32 v4, 48, v9
	s_movk_i32 s6, 0x3c0
	v_ashrrev_i32_e32 v2, 6, v9
	v_and_or_b32 v3, v3, s6, v4
	v_lshl_or_b32 v0, v0, 6, v4
	v_readlane_b32 s6, v250, 2
	v_lshlrev_b32_e32 v4, 2, v9
	v_lshl_add_u32 v5, v2, 10, s86
	v_add_lshl_u32 v2, v2, s6, 10
	v_and_b32_e32 v4, 32, v4
	v_ashrrev_i32_e32 v1, 1, v9
	v_bitop3_b32 v186, v0, v2, v4 bitop3:0xde
	v_lshlrev_b32_e32 v0, 14, v12
	v_and_b32_e32 v1, -8, v1
	v_readlane_b32 s6, v250, 1
	v_and_b32_e32 v0, 0xffff8000, v0
	v_lshl_add_u32 v0, v13, 11, v0
	v_add_u32_e32 v187, s6, v1
	v_and_b32_e32 v1, 1, v12
	v_lshl_or_b32 v0, v1, 6, v0
	v_lshl_add_u32 v168, v14, 1, v0
	v_lshlrev_b32_e32 v0, 14, v8
	v_lshlrev_b32_e32 v6, 2, v185
	v_and_b32_e32 v0, 0xffff8000, v0
	v_and_b32_e32 v6, 32, v6
	s_waitcnt vmcnt(6)
	s_cmpk_lt_u32 s33, 0x100
	v_lshl_add_u32 v0, v10, 11, v0
	v_and_b32_e32 v1, 1, v8
	v_bitop3_b32 v3, v3, v5, v6 bitop3:0xde
	s_cselect_b64 s[18:19], -1, 0
	v_lshl_or_b32 v0, v1, 6, v0
	s_add_i32 s65, 0, 0x10000
	s_add_i32 s66, 0, 0x14000
	s_ashr_i32 s63, s46, 31
	s_mov_b32 s64, s46
	v_mov_b32_e32 v169, v165
	v_lshl_add_u32 v170, v11, 1, v0
	v_mov_b32_e32 v171, v165
	v_mov_b64_e32 v[172:173], 0x580
	v_mov_b64_e32 v[174:175], 0x57f
	v_add_u32_e32 v188, s65, v186
	v_add_u32_e32 v189, s66, v186
	v_add_u32_e32 v190, 0, v3
	v_mov_b32_e32 v191, 0x358637bd
	s_mov_b32 s67, 0x800000
	s_mov_b32 s68, 0xc3e00000
	s_movk_i32 s69, 0x1600
	v_mov_b32_e32 v192, 0x43e00000
	s_barrier
	s_branch .LBB0_1064

.LBB0_1243:
	s_mov_b64 s[16:17], 0x80
	s_add_i32 m0, s40, 0x18000
	v_lshl_add_u64 v[6:7], v[6:7], 0, s[16:17]
	global_load_lds_dwordx4 v[6:7], off
	v_lshl_add_u64 v[4:5], v[4:5], 0, s[16:17]
	s_add_i32 m0, s40, 0x1a000
	s_add_i32 s65, s40, 0x8000
	s_add_i32 s66, s40, 0xa000
	s_sext_i32_i8 s64, s6
	global_load_lds_dwordx4 v[4:5], off
	v_lshl_add_u64 v[0:1], v[0:1], 0, s[16:17]
	s_mov_b32 m0, s65
	s_add_u32 s6, s28, 0xb0080
	global_load_lds_dwordx4 v[0:1], off
	v_lshl_add_u64 v[0:1], v[2:3], 0, s[16:17]
	s_mov_b32 m0, s66
	s_addc_u32 s7, s29, 0
	global_load_lds_dwordx4 v[0:1], off
	s_add_i32 m0, s40, 0x1c000
	v_lshl_add_u64 v[0:1], s[6:7], 0, v[170:171]
	global_load_lds_dwordx4 v[0:1], off
	v_lshl_add_u64 v[0:1], s[6:7], 0, v[174:175]
	s_add_i32 m0, s40, 0x1e000
	v_and_b32_e32 v189, 15, v186
	global_load_lds_dwordx4 v[0:1], off
	s_waitcnt vmcnt(8)
	s_barrier
	v_or_b32_e32 v14, s87, v189
	v_lshlrev_b32_e32 v15, 6, v14
	v_and_b32_e32 v15, 0x3c0, v15
	v_and_b32_e32 v188, 48, v186
	s_waitcnt vmcnt(0)
	v_and_b32_e32 v17, 0xfffffc00, v187
	v_lshlrev_b32_e32 v14, 2, v14
	v_and_b32_e32 v0, 0xffff0, v8
	v_or_b32_e32 v16, v15, v188
	v_add_u32_e32 v18, s86, v17
	v_and_b32_e32 v14, 32, v14
	v_readlane_b32 s4, v250, 8
	v_add_lshl_u32 v0, v9, v0, 12
	v_bitop3_b32 v191, v15, v14, v188 bitop3:0x36
	v_bitop3_b32 v14, v16, v18, v14 bitop3:0xde
	v_add_u32_e32 v16, s4, v17
	v_lshlrev_b32_e32 v17, 2, v186
	s_waitcnt vmcnt(6)
	v_lshl_add_u32 v162, v10, 1, v0
	v_and_b32_e32 v0, 0xffff0, v11
	v_lshl_or_b32 v15, v189, 6, v188
	v_and_b32_e32 v17, 32, v17
	s_cmpk_lt_u32 s33, 0x100
	v_add_lshl_u32 v0, v12, v0, 12
	v_bitop3_b32 v192, v15, v16, v17 bitop3:0xde
	s_cselect_b64 s[18:19], -1, 0
	v_lshl_add_u32 v164, v13, 1, v0
	v_mov_b32_e32 v163, v161
	v_mov_b32_e32 v165, v161
	v_mov_b64_e32 v[166:167], 0x100
	v_mov_b64_e32 v[168:169], 0xff
	v_add_u32_e32 v193, 0, v14
	v_mov_b32_e32 v32, v161
	v_mov_b32_e32 v33, v161
	v_mov_b32_e32 v34, v161
	v_mov_b32_e32 v35, v161
	v_mov_b32_e32 v36, v161
	v_mov_b32_e32 v37, v161
	v_mov_b32_e32 v38, v161
	v_mov_b32_e32 v39, v161
	v_mov_b32_e32 v48, v161
	v_mov_b32_e32 v49, v161
	v_mov_b32_e32 v50, v161
	v_mov_b32_e32 v51, v161
	v_mov_b32_e32 v52, v161
	v_mov_b32_e32 v53, v161
	v_mov_b32_e32 v54, v161
	v_mov_b32_e32 v55, v161
	v_mov_b32_e32 v64, v161
	v_mov_b32_e32 v65, v161
	v_mov_b32_e32 v66, v161
	v_mov_b32_e32 v67, v161
	v_mov_b32_e32 v68, v161
	v_mov_b32_e32 v69, v161
	v_mov_b32_e32 v70, v161
	v_mov_b32_e32 v71, v161
	v_mov_b32_e32 v80, v161
	v_mov_b32_e32 v81, v161
	v_mov_b32_e32 v82, v161
	v_mov_b32_e32 v83, v161
	v_mov_b32_e32 v84, v161
	v_mov_b32_e32 v85, v161
	v_mov_b32_e32 v86, v161
	v_mov_b32_e32 v87, v161
	v_mov_b32_e32 v40, v161
	v_mov_b32_e32 v41, v161
	v_mov_b32_e32 v42, v161
	v_mov_b32_e32 v43, v161
	v_mov_b32_e32 v44, v161
	v_mov_b32_e32 v45, v161
	v_mov_b32_e32 v46, v161
	v_mov_b32_e32 v47, v161
	v_mov_b32_e32 v56, v161
	v_mov_b32_e32 v57, v161
	v_mov_b32_e32 v58, v161
	v_mov_b32_e32 v59, v161
	v_mov_b32_e32 v60, v161
	v_mov_b32_e32 v61, v161
	v_mov_b32_e32 v62, v161
	v_mov_b32_e32 v63, v161
	v_mov_b32_e32 v72, v161
	v_mov_b32_e32 v73, v161
	v_mov_b32_e32 v74, v161
	v_mov_b32_e32 v75, v161
	v_mov_b32_e32 v76, v161
	v_mov_b32_e32 v77, v161
	v_mov_b32_e32 v78, v161
	v_mov_b32_e32 v79, v161
	v_mov_b32_e32 v88, v161
	v_mov_b32_e32 v89, v161
	v_mov_b32_e32 v90, v161
	v_mov_b32_e32 v91, v161
	v_mov_b32_e32 v92, v161
	v_mov_b32_e32 v93, v161
	v_mov_b32_e32 v94, v161
	v_mov_b32_e32 v95, v161
	v_mov_b32_e32 v96, v161
	v_mov_b32_e32 v97, v161
	v_mov_b32_e32 v98, v161
	v_mov_b32_e32 v99, v161
	v_mov_b32_e32 v100, v161
	v_mov_b32_e32 v101, v161
	v_mov_b32_e32 v102, v161
	v_mov_b32_e32 v103, v161
	v_mov_b32_e32 v112, v161
	v_mov_b32_e32 v113, v161
	v_mov_b32_e32 v114, v161
	v_mov_b32_e32 v115, v161
	v_mov_b32_e32 v116, v161
	v_mov_b32_e32 v117, v161
	v_mov_b32_e32 v118, v161
	v_mov_b32_e32 v119, v161
	v_mov_b32_e32 v128, v161
	v_mov_b32_e32 v129, v161
	v_mov_b32_e32 v130, v161
	v_mov_b32_e32 v131, v161
	v_mov_b32_e32 v132, v161
	v_mov_b32_e32 v133, v161
	v_mov_b32_e32 v134, v161
	v_mov_b32_e32 v135, v161
	v_mov_b32_e32 v144, v161
	v_mov_b32_e32 v145, v161
	v_mov_b32_e32 v146, v161
	v_mov_b32_e32 v147, v161
	v_mov_b32_e32 v148, v161
	v_mov_b32_e32 v149, v161
	v_mov_b32_e32 v150, v161
	v_mov_b32_e32 v151, v161
	v_mov_b32_e32 v104, v161
	v_mov_b32_e32 v105, v161
	v_mov_b32_e32 v106, v161
	v_mov_b32_e32 v107, v161
	v_mov_b32_e32 v108, v161
	v_mov_b32_e32 v109, v161
	v_mov_b32_e32 v110, v161
	v_mov_b32_e32 v111, v161
	v_mov_b32_e32 v120, v161
	v_mov_b32_e32 v121, v161
	v_mov_b32_e32 v122, v161
	v_mov_b32_e32 v123, v161
	v_mov_b32_e32 v124, v161
	v_mov_b32_e32 v125, v161
	v_mov_b32_e32 v126, v161
	v_mov_b32_e32 v127, v161
	v_mov_b32_e32 v136, v161
	v_mov_b32_e32 v137, v161
	v_mov_b32_e32 v138, v161
	v_mov_b32_e32 v139, v161
	v_mov_b32_e32 v140, v161
	v_mov_b32_e32 v141, v161
	v_mov_b32_e32 v142, v161
	v_mov_b32_e32 v143, v161
	v_mov_b32_e32 v152, v161
	v_mov_b32_e32 v153, v161
	v_mov_b32_e32 v154, v161
	v_mov_b32_e32 v155, v161
	v_mov_b32_e32 v156, v161
	v_mov_b32_e32 v157, v161
	v_mov_b32_e32 v158, v161
	v_mov_b32_e32 v159, v161
	s_barrier
	s_branch .LBB0_1246

.LBB0_1346:
	s_add_u32 s16, s50, 0x20000
	s_addc_u32 s17, s51, 0
	s_add_u32 s50, s50, 0x28000
	s_mov_b64 s[18:19], 0x80
	s_addc_u32 s51, s51, 0
	s_add_i32 m0, s42, 0x18000
	v_lshl_add_u64 v[6:7], v[6:7], 0, s[18:19]
	global_load_lds_dwordx4 v[6:7], off
	v_lshl_add_u64 v[4:5], v[4:5], 0, s[18:19]
	s_add_i32 m0, s42, 0x1a000
	s_add_i32 s54, s42, 0x8000
	s_add_i32 s55, s42, 0xa000
	global_load_lds_dwordx4 v[4:5], off
	v_lshl_add_u64 v[0:1], v[0:1], 0, s[18:19]
	s_mov_b32 m0, s54
	s_add_u32 s0, s36, 0x80080
	global_load_lds_dwordx4 v[0:1], off
	v_lshl_add_u64 v[0:1], v[2:3], 0, s[18:19]
	s_mov_b32 m0, s55
	s_addc_u32 s1, s37, 0
	global_load_lds_dwordx4 v[0:1], off
	s_add_i32 m0, s42, 0x1c000
	v_lshl_add_u64 v[0:1], s[0:1], 0, v[130:131]
	global_load_lds_dwordx4 v[0:1], off
	v_lshl_add_u64 v[0:1], s[0:1], 0, v[134:135]
	s_add_i32 m0, s42, 0x1e000
	v_and_b32_e32 v4, 48, v8
	global_load_lds_dwordx4 v[0:1], off
	s_waitcnt vmcnt(8)
	s_barrier
	v_and_b32_e32 v0, 15, v8
	v_or_b32_e32 v188, s87, v0
	v_ashrrev_i32_e32 v1, 4, v8
	v_lshlrev_b32_e32 v3, 6, v188
	s_movk_i32 s0, 0x3c0
	v_and_or_b32 v3, v3, s0, v4
	v_lshl_or_b32 v4, v0, 6, v4
	v_or_b32_e32 v0, v1, v0
	v_ashrrev_i32_e32 v2, 6, v8
	v_readlane_b32 s0, v250, 2
	v_cmp_eq_u32_e64 s[6:7], 0, v0
	v_lshlrev_b32_e32 v0, 15, v9
	v_lshl_add_u32 v5, v2, 10, s86
	v_add_lshl_u32 v2, v2, s0, 10
	v_readlane_b32 s0, v250, 1
	v_and_b32_e32 v0, 0xffff0000, v0
	v_lshl_add_u32 v0, v10, 12, v0
	v_lshl_add_u32 v190, v1, 3, s0
	v_and_b32_e32 v1, 1, v9
	v_lshlrev_b32_e32 v6, 2, v188
	v_lshl_or_b32 v0, v1, 6, v0
	v_and_b32_e32 v6, 32, v6
	v_lshl_add_u32 v136, v11, 1, v0
	v_lshlrev_b32_e32 v0, 15, v12
	v_bitop3_b32 v3, v3, v5, v6 bitop3:0xde
	v_lshlrev_b32_e32 v5, 2, v8
	v_and_b32_e32 v0, 0xffff0000, v0
	v_and_b32_e32 v5, 32, v5
	s_waitcnt vmcnt(6)
	s_cmpk_lt_u32 s33, 0x100
	v_lshl_add_u32 v0, v13, 12, v0
	v_and_b32_e32 v1, 1, v12
	v_bitop3_b32 v189, v4, v2, v5 bitop3:0xde
	s_cselect_b64 s[20:21], -1, 0
	v_lshl_or_b32 v0, v1, 6, v0
	s_add_i32 s57, 0, 0x10000
	s_add_i32 s60, 0, 0x14000
	v_cmp_gt_u32_e64 s[0:1], 16, v8
	s_ashr_i32 s33, s46, 31
	s_ashr_i32 s56, s2, 31
	v_mov_b32_e32 v137, v131
	v_lshl_add_u32 v138, v14, 1, v0
	v_mov_b32_e32 v139, v131
	v_mov_b64_e32 v[140:141], 0x100
	v_mov_b64_e32 v[142:143], 0xff
	v_add_u32_e32 v191, s57, v189
	v_add_u32_e32 v192, s60, v189
	v_add_u32_e32 v193, 0, v3
	v_mbcnt_hi_u32_b32 v194, -1, v225
	v_mov_b32_e32 v195, 0x358637bd
	s_mov_b32 s61, 0x800000
	s_barrier
	s_branch .LBB0_1349
